# in-proj schedule by workgroup class: 104 workgroups run four main units with no GEMM switch, the others two or one main units plus V^T / memory units and the weight conversion
# speedup vs baseline: 1.0169x; 1.0092x over previous
.LBB0_18:
	s_cmpk_lg_i32 s52, 0x100
	s_load_dwordx16 s[36:51], s[0:1], 0x0
	s_load_dwordx8 s[20:27], s[0:1], 0x40
	s_cselect_b64 s[0:1], -1, 0
	v_writelane_b32 v238, s0, 2
	s_cmpk_lt_i32 s2, 0x100
	s_mov_b32 s16, s2
	v_writelane_b32 v238, s1, 3
	s_cselect_b64 s[0:1], -1, 0
	v_writelane_b32 v238, s0, 4
	s_ashr_i32 s17, s2, 31
	s_ashr_i32 s97, s52, 31
	v_writelane_b32 v238, s1, 5
	s_lshr_b32 s0, s17, 29
	s_add_i32 s0, s2, s0
	s_ashr_i32 s7, s0, 3
	s_and_b32 s0, s0, -8
	s_sub_i32 s9, s2, s0
	s_lshl_b32 s8, s9, 5
	s_waitcnt lgkmcnt(0)
	s_cmp_eq_u64 s[36:37], 0
	s_cselect_b64 s[0:1], -1, 0
	v_writelane_b32 v238, s0, 6
	s_mul_i32 s6, s53, s52
	s_mov_b32 s96, s52
	v_writelane_b32 v238, s1, 7
	v_writelane_b32 v238, s20, 8
	s_cmp_eq_u64 s[26:27], 0
	s_cselect_b64 s[0:1], -1, 0
	v_writelane_b32 v238, s21, 9
	v_writelane_b32 v238, s22, 10
	v_writelane_b32 v238, s23, 11
	v_writelane_b32 v238, s24, 12
	v_writelane_b32 v238, s25, 13
	v_writelane_b32 v238, s26, 14
	v_writelane_b32 v238, s27, 15
	v_writelane_b32 v238, s0, 16
	s_cmpk_lt_i32 s2, 0x200
	v_mbcnt_lo_u32_b32 v0, -1, 0
	v_writelane_b32 v238, s1, 17
	s_cselect_b64 s[0:1], -1, 0
	v_writelane_b32 v238, s0, 18
	s_add_i32 s10, s52, -16
	v_mov_b32_e32 v1, 0
	v_writelane_b32 v238, s1, 19
	s_add_i32 s0, s2, 0x100
	s_and_b32 s1, s2, 3
	s_lshl_b32 s2, s2, 4
	v_writelane_b32 v238, s2, 20
	s_andn2_b32 s2, s2, 63
	s_ashr_i32 s3, s2, 31
	v_writelane_b32 v238, s2, 21
	v_mov_b32_e32 v205, 1
	v_mov_b32_e32 v206, 0x3727c5ac
	v_writelane_b32 v238, s3, 22
	s_lshl_b32 s2, s1, 6
	v_writelane_b32 v238, s2, 23
	s_lshl_b64 s[2:3], s[16:17], 14
	v_writelane_b32 v238, s2, 24
	s_lshl_b32 s1, s1, 7
	v_mov_b32_e32 v207, 0x260
	v_writelane_b32 v238, s3, 25
	v_writelane_b32 v238, s1, 26
	s_bitset1_b32 s1, 10
	v_writelane_b32 v238, s1, 27
	s_lshl_b32 s1, s0, 4
	s_and_b32 s2, s1, 0xffffffc0
	s_ashr_i32 s3, s2, 31
	v_writelane_b32 v238, s2, 28
	s_ashr_i32 s1, s0, 31
	s_lshl_b64 s[0:1], s[0:1], 14
	v_writelane_b32 v238, s3, 29
	v_writelane_b32 v238, s0, 30
	v_mov_b32_e32 v208, 0x358637bd
	v_writelane_b32 v238, s1, 31
	s_add_i32 s0, s16, 0xffffff30
	s_cmp_lt_u32 s0, 2
	s_cselect_b32 s0, s0, 0x1000000
	v_writelane_b32 v238, s0, 32
	s_not_b32 s0, s16
	s_add_i32 s0, s52, s0
	s_cmp_lt_u32 s16, 0x68
	s_cselect_b32 s0, 0x1000000, s0
	v_writelane_b32 v238, s0, 33
	s_add_i32 s0, s16, 0xffffff2e
	s_cmp_lt_u32 s0, 2
	s_cselect_b32 s0, s0, 0x1000000
	v_writelane_b32 v238, s0, 34
	s_add_i32 s0, s16, 0xffffff98
	s_cmp_lt_u32 s0, 0x68
	s_cselect_b32 s2, s0, -1
	s_add_i32 s0, s16, 0xffffff28
	s_add_i32 s1, s16, 0xffffff90
	s_cmp_lt_u32 s0, 40
	s_cselect_b32 s2, s1, s2
	s_lshl_b32 s60, s52, 3
	s_cmpk_eq_i32 s52, 0x100
	s_cselect_b64 s[0:1], -1, 0
	s_and_b64 s[10:11], s[0:1], exec
	s_cselect_b32 s10, s2, s16
	s_cselect_b32 s29, 0x480, s60
	s_cmp_lt_i32 s10, 0
	s_cselect_b64 s[18:19], -1, 0
	s_mov_b32 s3, 0
	s_mov_b32 s2, s16
	v_writelane_b32 v238, s18, 35
	s_mov_b32 s53, s3
	s_lshl_b32 s15, s10, 3
	v_writelane_b32 v238, s19, 36
	s_lshl_b64 s[18:19], s[2:3], 9
	s_lshl_b32 s62, s16, 3
	v_writelane_b32 v238, s18, 37
	s_lshl_b64 s[92:93], s[52:53], 9
	v_mov_b64_e32 v[186:187], 0x100
	v_writelane_b32 v238, s19, 38
	s_add_u32 s18, s84, 0x1aa00200
	s_addc_u32 s19, s85, 0
	v_writelane_b32 v238, s18, 39
	v_mov_b64_e32 v[188:189], 0xff
	v_mbcnt_hi_u32_b32 v209, -1, v0
	v_writelane_b32 v238, s19, 40
	s_add_u32 s18, s84, 0x1aa00400
	s_addc_u32 s19, s85, 0
	v_writelane_b32 v238, s18, 41
	v_mov_b32_e32 v210, 2
	v_mov_b32_e32 v211, 4
	v_writelane_b32 v238, s19, 42
	s_add_u32 s18, s84, 0x1aa00500
	s_addc_u32 s19, s85, 0
	v_writelane_b32 v238, s18, 43
	v_mov_b32_e32 v212, 3
	v_mov_b32_e32 v213, 0x41b17218
	v_writelane_b32 v238, s19, 44
	s_add_u32 s18, s84, 0x1aa00600
	s_addc_u32 s19, s85, 0
	v_writelane_b32 v238, s18, 45
	v_mov_b32_e32 v214, 0x9800000
	v_mov_b32_e32 v215, 0x9000000
	v_writelane_b32 v238, s19, 46
	s_add_u32 s18, s84, 0x1aa00700
	s_addc_u32 s19, s85, 0
	v_writelane_b32 v238, s18, 47
	s_movk_i32 s59, 0x2a00
	s_mov_b32 s89, 0x800000
	v_writelane_b32 v238, s19, 48
	s_add_u32 s18, s84, 0x1aa00800
	s_addc_u32 s19, s85, 0
	v_writelane_b32 v238, s18, 49
	s_mov_b64 s[20:21], 0x80
	s_mov_b32 s34, 0x3e0293ee
	v_writelane_b32 v238, s19, 50
	s_add_u32 s18, s84, 0x1aa00900
	s_addc_u32 s19, s85, 0
	v_writelane_b32 v238, s18, 51
	s_mov_b32 s88, 0x3f803f80
	s_nop 0
	v_writelane_b32 v238, s19, 52
	s_add_u32 s18, s84, 0x1aa00a00
	s_addc_u32 s19, s85, 0
	v_writelane_b32 v238, s18, 53
	s_nop 1
	v_writelane_b32 v238, s19, 54
	s_add_u32 s18, s84, 0x1aa00b00
	s_addc_u32 s19, s85, 0
	v_writelane_b32 v238, s18, 55
	s_nop 1
	v_writelane_b32 v238, s19, 56
	s_add_u32 s18, s84, 0x1aa00c00
	s_addc_u32 s19, s85, 0
	v_writelane_b32 v238, s18, 57
	s_nop 1
	v_writelane_b32 v238, s19, 58
	s_add_u32 s18, s84, 0x1aa00d00
	s_addc_u32 s19, s85, 0
	v_writelane_b32 v238, s18, 59
	s_nop 1
	v_writelane_b32 v238, s19, 60
	s_add_u32 s18, s84, 0x1aa00e00
	s_addc_u32 s19, s85, 0
	v_writelane_b32 v238, s18, 61
	s_nop 1
	v_writelane_b32 v238, s19, 62
	s_add_u32 s18, s84, 0x1aa00f00
	s_addc_u32 s19, s85, 0
	v_writelane_b32 v238, s18, 63
	s_nop 1
	v_writelane_b32 v237, s19, 0
	s_add_u32 s18, s84, 0x1aa01000
	s_addc_u32 s19, s85, 0
	v_writelane_b32 v237, s18, 1
	s_nop 1
	v_writelane_b32 v237, s19, 2
	s_add_u32 s18, s84, 0x1aa01100
	s_addc_u32 s19, s85, 0
	v_writelane_b32 v237, s18, 3
	s_nop 1
	v_writelane_b32 v237, s19, 4
	s_add_u32 s18, s84, 0x1aa01200
	s_addc_u32 s19, s85, 0
	v_writelane_b32 v237, s18, 5
	s_nop 1
	v_writelane_b32 v237, s19, 6
	s_add_u32 s18, s84, 0x1aa01300
	s_addc_u32 s19, s85, 0
	v_writelane_b32 v237, s18, 7
	s_cmp_eq_u32 s13, 15
	s_nop 0
	v_writelane_b32 v237, s19, 8
	s_cselect_b64 s[18:19], -1, 0
	v_writelane_b32 v237, s18, 9
	s_cmp_eq_u32 s13, 14
	s_nop 0
	v_writelane_b32 v237, s19, 10
	s_cselect_b64 s[18:19], -1, 0
	v_writelane_b32 v237, s18, 11
	s_cmp_eq_u32 s13, 13
	s_nop 0
	v_writelane_b32 v237, s19, 12
	s_cselect_b64 s[18:19], -1, 0
	v_writelane_b32 v237, s18, 13
	s_cmp_eq_u32 s13, 12
	s_nop 0
	v_writelane_b32 v237, s19, 14
	s_cselect_b64 s[18:19], -1, 0
	v_writelane_b32 v237, s18, 15
	s_cmp_eq_u32 s13, 11
	s_nop 0
	v_writelane_b32 v237, s19, 16
	s_cselect_b64 s[18:19], -1, 0
	v_writelane_b32 v237, s18, 17
	s_cmp_eq_u32 s13, 10
	s_nop 0
	v_writelane_b32 v237, s19, 18
	s_cselect_b64 s[18:19], -1, 0
	v_writelane_b32 v237, s18, 19
	s_cmp_eq_u32 s13, 9
	s_nop 0
	v_writelane_b32 v237, s19, 20
	s_cselect_b64 s[18:19], -1, 0
	v_writelane_b32 v237, s18, 21
	s_cmp_eq_u32 s13, 8
	s_nop 0
	v_writelane_b32 v237, s19, 22
	s_cselect_b64 s[18:19], -1, 0
	v_writelane_b32 v237, s18, 23
	s_cmp_eq_u32 s13, 7
	s_nop 0
	v_writelane_b32 v237, s19, 24
	s_cselect_b64 s[18:19], -1, 0
	v_writelane_b32 v237, s18, 25
	s_cmp_eq_u32 s13, 6
	s_nop 0
	v_writelane_b32 v237, s19, 26
	s_cselect_b64 s[18:19], -1, 0
	v_writelane_b32 v237, s18, 27
	s_cmp_eq_u32 s13, 5
	s_nop 0
	v_writelane_b32 v237, s19, 28
	s_cselect_b64 s[18:19], -1, 0
	v_writelane_b32 v237, s18, 29
	s_cmp_eq_u32 s13, 4
	s_nop 0
	v_writelane_b32 v237, s19, 30
	s_cselect_b64 s[18:19], -1, 0
	v_writelane_b32 v237, s18, 31
	s_cmp_eq_u32 s13, 3
	s_nop 0
	v_writelane_b32 v237, s19, 32
	s_cselect_b64 s[18:19], -1, 0
	v_writelane_b32 v237, s18, 33
	s_cmp_eq_u32 s13, 2
	s_nop 0
	v_writelane_b32 v237, s19, 34
	s_cselect_b64 s[18:19], -1, 0
	v_writelane_b32 v237, s18, 35
	s_cmp_eq_u32 s13, 1
	s_nop 0
	v_writelane_b32 v237, s19, 36
	s_cselect_b64 s[18:19], -1, 0
	v_writelane_b32 v237, s18, 37
	s_cmp_eq_u32 s13, 0
	s_nop 0
	v_writelane_b32 v237, s19, 38
	s_cselect_b64 s[18:19], -1, 0
	s_lshl_b32 s11, s13, 8
	s_add_u32 s4, s4, s11
	s_addc_u32 s5, s5, 0
	v_writelane_b32 v237, s18, 39
	s_add_u32 s12, s4, 0x1400
	s_addc_u32 s13, s5, 0
	v_writelane_b32 v237, s19, 40
	v_writelane_b32 v237, s12, 41
	s_add_u32 s4, s4, 0x2400
	s_addc_u32 s5, s5, 0
	v_writelane_b32 v237, s13, 42
	v_writelane_b32 v237, s4, 43
	s_nop 1
	v_writelane_b32 v237, s5, 44
	s_add_u32 s4, s84, 0x1aa03400
	s_addc_u32 s5, s85, 0
	v_writelane_b32 v237, s4, 45
	s_nop 1
	v_writelane_b32 v237, s5, 46
	s_add_u32 s4, s84, 0x1aa03500
	s_addc_u32 s5, s85, 0
	v_writelane_b32 v237, s4, 47
	s_cmp_lt_i32 s9, 0
	s_mul_i32 s9, s9, 33
	v_writelane_b32 v237, s5, 48
	s_cselect_b32 s4, s9, s8
	s_add_i32 s4, s4, s7
	s_ashr_i32 s5, s4, 31
	s_lshr_b32 s5, s5, 26
	s_add_i32 s5, s4, s5
	s_and_b32 s7, s5, 0xffc0
	s_sub_i32 s4, s4, s7
	s_bfe_i32 s7, s4, 0x80000
	s_bfe_u32 s7, s7, 0x3000c
	s_add_i32 s7, s4, s7
	s_and_b32 s8, s7, 0xf8
	s_sub_i32 s4, s4, s8
	s_ashr_i32 s5, s5, 6
	s_bfe_i32 s7, s7, 0x80000
	s_lshl_b32 s5, s5, 3
	s_sext_i32_i16 s7, s7
	s_sext_i32_i8 s4, s4
	s_add_i32 s12, s5, s4
	s_ashr_i32 s4, s7, 3
	v_writelane_b32 v237, s4, 49
	s_lshr_b32 s4, s7, 3
	s_bfe_i64 s[4:5], s[4:5], 0x100000
	s_lshl_b64 s[4:5], s[4:5], 20
	v_writelane_b32 v237, s4, 50
	s_mov_b32 s8, s12
	s_ashr_i32 s13, s12, 31
	v_writelane_b32 v237, s5, 51
	s_lshl_b32 s4, s10, 8
	v_writelane_b32 v237, s4, 52
	s_lshl_b32 s4, s16, 7
	v_writelane_b32 v237, s4, 53
	s_lshl_b32 s4, s16, 5
	v_writelane_b32 v237, s4, 54
	v_writelane_b32 v237, s15, 55
	s_add_i32 s4, s29, s15
	v_writelane_b32 v237, s4, 56
	v_writelane_b32 v237, s16, 57
	s_lshl_b32 s4, s16, 8
	s_ashr_i32 s61, s60, 31
	v_writelane_b32 v237, s17, 58
	v_writelane_b32 v237, s4, 59
	s_lshl_b32 s4, s52, 8
	v_writelane_b32 v237, s4, 60
	s_add_i32 s4, s62, s60
	v_writelane_b32 v237, s4, 61
	s_lshl_b32 s4, s52, 6
	v_writelane_b32 v237, s4, 62
	v_writelane_b32 v237, s8, 63
	s_lshl_b64 s[4:5], s[2:3], 14
	s_lshl_b32 s63, s52, 4
	v_writelane_b32 v236, s9, 0
	s_lshl_b64 s[8:9], s[12:13], 20
	v_writelane_b32 v236, s8, 1
	s_lshl_b32 s30, s52, 7
	s_lshl_b32 s35, s52, 5
	v_writelane_b32 v236, s9, 2
	s_lshl_b64 s[8:9], s[96:97], 14
	v_writelane_b32 v236, s8, 3
	s_lshl_b32 s33, s29, 5
	s_lshl_b32 s58, s29, 3
	v_writelane_b32 v236, s9, 4
	s_lshl_b64 s[8:9], s[2:3], 13
	s_or_b32 s4, s4, 16
	s_lshl_b64 s[94:95], s[60:61], 12
	s_lshl_b64 s[98:99], s[60:61], 13
	v_writelane_b32 v236, s8, 5
	s_lshl_b64 s[26:27], s[52:53], 13
	s_mov_b32 s2, s52
	v_writelane_b32 v236, s9, 6
	s_add_u32 s8, s36, s4
	s_addc_u32 s9, s37, s5
	v_writelane_b32 v236, s8, 7
	s_lshl_b64 s[12:13], s[52:53], 14
	s_add_u32 s4, s38, s4
	v_writelane_b32 v236, s9, 8
	v_writelane_b32 v236, s2, 9
	s_movk_i32 s61, 0x1000
	s_nop 0
	v_writelane_b32 v236, s3, 10
	v_writelane_b32 v236, s36, 11
	s_addc_u32 s5, s39, s5
	s_mul_i32 s2, s6, s14
	v_writelane_b32 v236, s37, 12
	v_writelane_b32 v236, s38, 13
	v_writelane_b32 v236, s39, 14
	v_writelane_b32 v236, s40, 15
	v_writelane_b32 v236, s41, 16
	v_writelane_b32 v236, s42, 17
	v_writelane_b32 v236, s43, 18
	v_writelane_b32 v236, s44, 19
	v_writelane_b32 v236, s45, 20
	v_writelane_b32 v236, s46, 21
	v_writelane_b32 v236, s47, 22
	v_writelane_b32 v236, s48, 23
	v_writelane_b32 v236, s49, 24
	v_writelane_b32 v236, s50, 25
	v_writelane_b32 v236, s51, 26
	v_writelane_b32 v236, s4, 27
	s_xor_b64 s[0:1], s[0:1], -1
	s_nop 0
	v_writelane_b32 v236, s5, 28
	v_writelane_b32 v236, s2, 29
	v_writelane_b32 v236, s0, 30
	s_nop 1
	v_writelane_b32 v236, s1, 31
	s_add_i32 s0, 0, 0x14400
	v_writelane_b32 v236, s0, 32
	s_add_i32 s0, 0, 0x18c00
	v_writelane_b32 v236, s0, 33
	s_add_i32 s0, 0, 0x23fc0
	v_writelane_b32 v236, s0, 34
	s_add_i32 s0, 0, 0x23fc4
	v_writelane_b32 v236, s0, 35
	s_mov_b32 s0, s60
	v_writelane_b32 v236, s0, 36
	s_nop 1
	v_writelane_b32 v236, s1, 37
	v_writelane_b32 v236, s58, 38
	v_writelane_b32 v236, s94, 39
	s_nop 1
	v_writelane_b32 v236, s95, 40
	v_writelane_b32 v236, s33, 41
	v_writelane_b32 v236, s35, 42
	s_branch .LBB0_23

.LBB0_462:
	s_add_i32 s67, s67, 1
	s_mov_b32 s36, 0x1000000
	s_mov_b32 s37, 0
	s_cmp_lg_u32 s86, 0
	s_cbranch_scc1 .Lnx_gi1
	s_movk_i32 s19, 0x68
	s_movk_i32 s38, 0x1d0
	s_cmp_eq_u32 s67, 1
	s_cselect_b32 s19, 0xd0, s19
	s_cselect_b32 s38, 0x100, s38
	s_cmp_eq_u32 s67, 3
	s_cselect_b32 s38, 0x238, s38
	s_cmp_lt_u32 s67, 4
	s_cselect_b32 s19, s19, 0
	s_cmp_lt_u32 s84, s19
	s_cbranch_scc0 .Lnx_done
	s_add_i32 s36, s38, s84
	s_branch .Lnx_done
.Lnx_gi1:
	s_cmp_lg_u32 s86, 1
	s_cbranch_scc1 .Lnx_done
	s_cmp_eq_u32 s67, 1
	s_cselect_b32 s19, 40, 0
	s_cmp_lt_u32 s84, s19
	s_cbranch_scc0 .Lnx_done
	s_add_i32 s36, s84, 0x98
.Lnx_done:
	v_mov_b64_e32 v[2:3], s[2:3]
	v_cmp_ge_i64_e32 vcc, s[36:37], v[2:3]
	v_cmp_lt_i64_e64 s[38:39], s[36:37], v[2:3]
	s_cbranch_vccnz .LBB0_468
	s_ashr_i32 s18, s36, 31
	s_lshr_b32 s18, s18, 29
	s_add_i32 s37, s36, s18
	s_and_b32 s18, s37, -8
	s_sub_i32 s36, s36, s18
	s_cmp_ge_i32 s36, s87
	s_mov_b64 s[18:19], -1
	s_cbranch_scc0 .LBB0_465
	s_sub_i32 s18, s36, s87
	s_mul_i32 s18, s18, s85
	s_add_i32 s69, s18, s15
	s_mov_b64 s[18:19], 0
